# v11 with the GEMM code placed 36 bytes later (dead s_nop padding after an unconditional branch): code-placement scan picked this offset
# speedup vs baseline: 1.0032x; 1.0032x over previous
.LBB0_358:
	v_lshlrev_b32_e32 v13, 2, v189
	v_lshl_or_b32 v194, s3, 6, v189
	v_lshl_or_b32 v12, v189, 6, v191
	s_lshl_b32 s3, s3, 13
	v_and_b32_e32 v13, 32, v13
	s_add_i32 m0, s45, 0x18000
	v_lshl_add_u64 v[0:1], v[0:1], 0, s[36:37]
	v_bitop3_b32 v12, v12, s3, v13 bitop3:0xde
	s_lshl_b32 s3, s10, 5
	s_waitcnt vmcnt(2)
	s_barrier
	global_load_lds_dwordx4 v[0:1], off
	v_lshl_add_u64 v[0:1], v[2:3], 0, s[36:37]
	s_add_i32 m0, s45, 0x1a000
	s_add_i32 s10, s45, 0x8000
	global_load_lds_dwordx4 v[0:1], off
	v_lshl_add_u64 v[0:1], v[8:9], 0, s[36:37]
	s_mov_b32 m0, s10
	s_add_i32 s11, s45, 0xa000
	global_load_lds_dwordx4 v[0:1], off
	v_lshl_add_u64 v[0:1], v[10:11], 0, s[36:37]
	s_mov_b32 m0, s11
	s_and_b32 s3, s3, 0x60
	global_load_lds_dwordx4 v[0:1], off
	s_add_i32 m0, s45, 0x1c000
	v_lshl_add_u64 v[0:1], v[4:5], 0, s[36:37]
	global_load_lds_dwordx4 v[0:1], off
	v_lshl_add_u64 v[0:1], v[6:7], 0, s[36:37]
	s_add_i32 m0, s45, 0x1e000
	s_add_i32 s13, s31, -2
	global_load_lds_dwordx4 v[0:1], off
	s_cmpk_lt_u32 s2, 0x100
	v_lshl_or_b32 v195, s3, 7, v192
	s_cselect_b64 s[74:75], -1, 0
	v_or_b32_e32 v196, s3, v190
	s_lshl_b32 s3, s82, 3
	v_cvt_f32_u32_e32 v0, s3
	s_lshr_b32 s2, s73, 3
	s_and_b32 s85, s73, 6
	s_add_i32 s58, s2, 1
	v_rcp_iflag_f32_e32 v0, v0
	s_cmp_lg_u64 s[42:43], 0
	s_cselect_b64 s[90:91], -1, 0
	s_cselect_b32 s100, s42, s88
	s_cselect_b32 s101, s43, s89
	s_sub_i32 s14, 0, s3
	v_mul_f32_e32 v0, 0x4f7ffffe, v0
	v_cvt_u32_f32_e32 v0, v0
	s_waitcnt vmcnt(6)
	v_mov_b32_e32 v157, v155
	s_mov_b32 s84, s2
	v_readfirstlane_b32 s15, v0
	s_mul_i32 s14, s14, s15
	s_mul_hi_u32 s14, s15, s14
	v_lshl_add_u64 v[164:165], s[42:43], 0, v[156:157]
	s_mov_b32 s18, 0
	s_add_i32 s33, s15, s14
	v_lshl_add_u64 v[166:167], s[8:9], 0, v[158:159]
	v_lshl_add_u64 v[168:169], s[8:9], 0, v[160:161]
	v_add_u32_e32 v157, 0, v12
	s_movk_i32 s69, 0x2000
	s_barrier
	v_lshlrev_b32_e32 v248, 4, v199
	s_branch .LBB0_361
	s_nop 0
	s_nop 0
	s_nop 0
	s_nop 0
	s_nop 0
	s_nop 0
	s_nop 0
	s_nop 0
	s_nop 0
